# v091 + one static s_setprio 1 for the younger half (waves 4-7) during the mLSTM and RG-LRU phases, reset to 0 at phase end
# baseline (speedup 1.0000x reference)
; #define LAS __attribute__((address_space(3)))
; DI unsigned pk2(float a, float b) { f32x2 v = {a, b}; bf2_t r = __builtin_convertvector(v, bf2_t); return __builtin_bit_cast(unsigned, r); }
; DI int opq(int x) { asm volatile("" : "+v"(x)); return x; }
; DI void phase_mlstm(const Params& p, unsigned char* shm, const int vb) {
;     ...
;                 const int lane = opq(threadIdx.x) & 63, fr = lane & 15, fq = lane >> 4;
;                 const int ti = w & 3;
; #pragma unroll
;                 for (int z = 0; z < 2; ++z) {
;                     const int si = 2 * (w >> 2) + z;
;                     f32x4 a4 = {0.f, 0.f, 0.f, 0.f};
;                     if (si <= ti) {
;                         const int ka = KI + (16 * si + fr) * RS + 16 * fq, qa = QI + (16 * ti + fr) * RS + 16 * fq;
; #pragma unroll
;                         for (int kk = 0; kk < 8; ++kk) {
;                             const bf16x8 af = *(const LAS bf16x8*)(lds + ka + 64 * kk);
;                             const bf16x8 bq = *(const LAS bf16x8*)(lds + qa + 64 * kk);
;                             a4 = __builtin_amdgcn_mfma_f32_16x16x32_bf16(af, bq, a4, 0, 0, 0);
;                         }
;                         const int t = 16 * ti + fr; const float Pt = Pc[t];
;                         const f32x4 qs = *(const LAS f32x4*)(Qc + 16 * si + 4 * fq);
;                         float rsm = 0.f;
; #pragma unroll
;                         for (int j = 0; j < 4; ++j) { const int s = 16 * si + 4 * fq + j; const float wg = (s <= t) ? __expf(Pt + qs[j]) : 0.f; a4[j] *= wg; rsm += a4[j]; }
;                         rsm += __shfl_xor(rsm, 16); rsm += __shfl_xor(rsm, 32);
;                         if (fq == 0) __hip_atomic_fetch_add((float*)(shm + RSUM) + t, rsm, __ATOMIC_RELAXED, __HIP_MEMORY_SCOPE_WORKGROUP);
;                     }
;                     u32x2 sm; sm[0] = pk2(a4[0], a4[1]); sm[1] = pk2(a4[2], a4[3]);
;                     *(LAS u32x2*)(lds + SMI + (16 * ti + fr) * SMS + (16 * si + 4 * fq) * 2) = sm;
;                 }
;                 if (w == 4 || w == 5) {
; #pragma unroll
;                     for (int z = 0; z < 2; ++z) {
;                         const int tn = 2 * (w - 4) + z;
;                         const int ka = KI + (64 + fr) * RS + 16 * fq, qa = QI + (16 * tn + fr) * RS + 16 * fq;
.LBB0_384:
	v_readlane_b32 s2, v245, 27
	v_readlane_b32 s3, v245, 28
	s_and_b64 vcc, exec, s[2:3]
	v_readfirstlane_b32 s33, v192
	s_cbranch_vccnz .LBB0_419
	s_cmp_ge_u32 s33, 0x100
	s_cbranch_scc0 .Lprio4_done
	s_setprio 1
.Lprio4_done:
	s_bfe_u32 s2, s33, 0x20006
	s_lshr_b32 s3, s33, 7
	s_lshr_b32 s0, s33, 6
	s_and_b32 s15, s3, 0x1fffffe
	s_lshl_b32 s22, s2, 4
	s_and_b32 s23, s33, 0xffffff80
	s_cmpk_eq_i32 s23, 0x100
	s_cselect_b64 s[28:29], -1, 0
	s_lshl_b32 s23, s0, 5
	s_andn2_b32 s33, s33, 63
	s_cmp_le_u32 s15, s2
	s_cselect_b64 s[30:31], -1, 0
	s_lshl_b32 s92, s15, 4
	s_lshl_b32 s90, s15, 5
	s_or_b32 s0, s3, 1
	s_cmp_le_u32 s0, s2
	s_cselect_b64 s[34:35], -1, 0
	s_lshl_b32 s38, s0, 4
	s_lshl_b32 s54, s0, 5
	s_add_i32 s55, s23, 0xffffff80
	s_add_i32 s40, s23, 0xffffff90
	s_mov_b32 s41, s62
	s_mov_b32 s27, s78
	s_branch .LBB0_387

; DI unsigned xb_add(unsigned* p, unsigned v) { return __hip_atomic_fetch_add(p, v, __ATOMIC_RELAXED, __HIP_MEMORY_SCOPE_AGENT); }
; DI void xcd_barrier(const XcdBarrier& b) {
;     asm volatile("s_waitcnt vmcnt(0)" ::: "memory");
;     __syncthreads();
;     if (threadIdx.x == 0) {
;         unsigned* bar = b.bar;
;         __builtin_amdgcn_s_waitcnt(0);
;         unsigned nloc = b.st[0], nx = b.st[1];
;         if (nloc == 0u) { xcd_barrier_complete(bar, b.x, nloc, nx); b.st[0] = nloc; b.st[1] = nx; }
;         const unsigned old = xb_add(&bar[XB_XSUB(b.x)], 1u);
;         const unsigned gen = old / nloc;
;         if (old + 1u == (gen + 1u) * nloc) {
.LBB0_419:
	s_setprio 0
	s_waitcnt vmcnt(0)
	v_readlane_b32 s8, v244, 3
	v_readlane_b32 s9, v244, 4
	s_barrier
	s_and_saveexec_b64 s[2:3], s[8:9]
	s_cbranch_execz .LBB0_383
	v_mov_b32_e32 v0, s63
	s_waitcnt vmcnt(0) expcnt(0) lgkmcnt(0)
	ds_read_b32 v2, v0
	v_mov_b32_e32 v0, s68
	ds_read_b32 v0, v0
	s_waitcnt lgkmcnt(1)
	v_cmp_ne_u32_e32 vcc, 0, v2
	s_cbranch_vccnz .LBB0_435
	s_mov_b32 s0, 1
	s_branch .LBB0_423

; #define LAS __attribute__((address_space(3)))
; DI int opq(int x) { asm volatile("" : "+v"(x)); return x; }
; DI void phase_rglru(const Params& p, unsigned char* shm) {
;     ...
;     const int tid = opq(threadIdx.x), lane = tid & 63, w = __builtin_amdgcn_readfirstlane(tid >> 6), fr = lane & 15, fq = lane >> 4;
;     const bf16_t* XRg = (const bf16_t*)(p.ws + WS_RA); const bf16_t* Gg = (const bf16_t*)(p.ws + WS_RC); bf16_t* Y = (bf16_t*)(p.ws + WS_RB);
;     const bf16_t* WG2 = (const bf16_t*)(p.ws + WS_WT_G); const float* SPp = (const float*)(p.ws + WS_SP);
;     LAS float* cw = (LAS float*)(lds + CW); LAS float* gb = (LAS float*)(lds + GB);
;     for (int unit = blockIdx.x; unit < 256; unit += gridDim.x) {
;         const int b = unit >> 3, blk = unit & 7, cg0 = blk * 192;
;         __syncthreads();
;         for (int i = tid; i < 960; i += 512) { const int j = i / 192, c = i % 192; cw[i] = j < 4 ? p.in[15][j * 1536 + cg0 + c] : p.in[16][cg0 + c]; }
;         for (int i = tid; i < 576; i += 512) { const int k = i / 192, c = i % 192; gb[i] = (k == 0 ? p.in[18] : (k == 1 ? p.in[20] : SPp))[cg0 + c]; }
;         if (tid < 72) *(LAS u32x4*)(lds + XR + (tid / 24) * TR + (tid % 24) * 16) = (u32x4){0u, 0u, 0u, 0u};
;         bf16x8 Bf[4][6];
;         const int chb = w < 4 ? 32 * w : 128 + 16 * (w - 4);
;         {
; #pragma unroll
;           for (int nt = 0; nt < 4; ++nt)
; #pragma unroll
;               for (int kk = 0; kk < 6; ++kk) {
;                   const int chn = chb + ((w < 4) ? 16 * (nt & 1) : 0) + fr;
;                   Bf[nt][kk] = *(const bf16x8*)(WG2 + ((size_t)((blk * 2 + (nt >> 1)) * 192 + chn) * 192 + 32 * kk + 8 * fq)); } }
;         int goff[3], loff[3];
; #pragma unroll
;         for (int j = 0; j < 3; ++j) { const int q = tid + 512 * j, row = q / 24, cc = q % 24; goff[j] = row * 1536 + cc * 8; loff[j] = row * TR + cc * 16; }
;         const size_t base = (size_t)b * S_ * 1536 + cg0;
;         u32x4 rx[3], rg[3];
; #pragma unroll
;         for (int j = 0; j < 3; ++j) { rx[j] = *(const u32x4*)(XRg + base + goff[j]); rg[j] = *(const u32x4*)(Gg + base + goff[j]); }
.LBB0_814:
	v_mov_b32_e32 v154, v192
	s_and_b64 vcc, exec, s[40:41]
	v_readfirstlane_b32 s0, v154
	s_cbranch_vccnz .LBB0_854
	s_cmp_ge_u32 s0, 0x100
	s_cbranch_scc0 .Lprio10_done
	s_setprio 1
.Lprio10_done:
	v_mul_hi_i32 v2, v154, s71
	v_lshrrev_b32_e32 v3, 31, v2
	v_ashrrev_i32_e32 v2, 2, v2
	s_movk_i32 s1, 0x3c0
	v_add_u32_e32 v2, v2, v3
	s_ashr_i32 s0, s0, 6
	v_cmp_gt_i32_e64 s[42:43], s1, v154
	s_movk_i32 s1, 0x240
	v_mul_lo_u32 v4, v2, 24
	v_cmp_gt_i32_e64 s[44:45], s1, v154
	v_mul_lo_u32 v3, v2, s72
	v_sub_u32_e32 v4, v154, v4
	s_lshl_b32 s1, s0, 4
	v_mul_lo_u32 v2, v2, s73
	v_add_u32_e32 v155, 0x200, v154
	s_lshl_b32 s2, s0, 5
	s_add_i32 s3, s1, 64
	v_lshl_add_u32 v158, v4, 3, v2
	v_mul_hi_i32 v2, v155, s71
	s_cmp_lt_i32 s0, 4
	v_lshrrev_b32_e32 v9, 31, v2
	v_ashrrev_i32_e32 v2, 2, v2
	s_cselect_b64 s[12:13], -1, 0
	v_add_u32_e32 v2, v2, v9
	s_and_b64 s[0:1], s[12:13], exec
	v_mul_lo_u32 v9, v2, 24
	v_and_b32_e32 v0, 15, v154
	s_cselect_b32 s0, s2, s3
	v_sub_u32_e32 v9, v155, v9
	v_mul_lo_u32 v10, v2, s73
	v_bfe_u32 v1, v154, 4, 2
	v_or_b32_e32 v175, s0, v0
	v_readlane_b32 s0, v244, 18
	v_lshl_add_u32 v160, v9, 3, v10
	v_add_u32_e32 v10, 0x400, v154
	v_lshlrev_b32_e32 v152, 4, v1
	v_readlane_b32 s1, v244, 19
	v_mul_hi_i32 v11, v10, s71
	v_lshrrev_b32_e32 v12, 31, v11
	v_lshl_add_u64 v[156:157], s[0:1], 0, v[152:153]
	s_movk_i32 s0, 0xbf
	v_ashrrev_i32_e32 v11, 2, v11
	v_cmp_lt_i32_e64 s[48:49], s0, v154
	v_add_u32_e32 v7, 0xffffff00, v154
	s_movk_i32 s0, 0xab
	v_add_u32_e32 v11, v11, v12
	v_max_i32_e32 v15, 64, v154
	v_max_i32_e32 v17, 0x1c0, v154
	v_lshlrev_b32_e32 v5, 4, v4
	v_cmp_gt_u32_e64 s[50:51], s70, v7
	v_mul_lo_u16_sdwa v7, v154, s0 dst_sel:DWORD dst_unused:UNUSED_PAD src0_sel:BYTE_0 src1_sel:DWORD
	v_mul_lo_u32 v12, v11, 24
	v_lshlrev_b32_e32 v4, 5, v4
	v_sub_u32_e32 v15, v15, v154
	v_sub_u32_e32 v17, v17, v154
	v_lshrrev_b16_e32 v7, 12, v7
	v_sub_u32_e32 v10, v10, v12
	v_mul_lo_u32 v12, v11, s73
	v_add_u32_e32 v178, s74, v4
	v_add_u32_e32 v179, s75, v4
	v_lshlrev_b32_e32 v4, 5, v9
	v_add_u32_e32 v15, 0x1ff, v15
	v_add_u32_e32 v17, 0x1ff, v17
	v_mul_lo_u16_e32 v8, 24, v7
	v_lshl_add_u32 v162, v10, 3, v12
	v_add_u32_e32 v180, s74, v4
	v_add_u32_e32 v181, s75, v4
	v_lshlrev_b32_e32 v4, 5, v10
	v_and_b32_e32 v177, 0xfffffff0, v175
	v_add_u32_e32 v177, v177, v175
	v_add_u32_e32 v177, 0xffffff10, v177
	v_add_u32_e32 v12, 16, v175
	v_cndmask_b32_e64 v12, v177, v12, s[12:13]
	v_mov_b32_e32 v177, v12
	v_lshrrev_b32_e32 v16, 9, v15
	v_lshrrev_b32_e32 v18, 9, v17
	v_sub_u16_e32 v8, v154, v8
	s_cselect_b32 s0, 16, 0
	v_mul_lo_u32 v2, v2, s72
	v_mul_lo_u32 v11, v11, s72
	v_add_u32_e32 v182, s74, v4
	v_add_u32_e32 v183, s75, v4
	v_lshlrev_b32_e32 v4, 1, v175
	v_lshl_add_u32 v185, v12, 2, s76
	v_lshlrev_b32_e32 v12, 1, v12
	v_add_u32_e32 v16, 1, v16
	v_add_u32_e32 v18, 1, v18
	v_add_u32_e32 v3, 0, v3
	v_add_u32_e32 v6, 0, v152
	v_mad_u32_u24 v7, v7, s72, 0
	v_lshlrev_b32_sdwa v8, v173, v8 dst_sel:DWORD dst_unused:UNUSED_PAD src0_sel:DWORD src1_sel:BYTE_0
	v_lshl_add_u32 v2, v9, 4, v2
	v_lshl_add_u32 v11, v10, 4, v11
	v_mul_u32_u24_e32 v0, 0x190, v0
	v_add_u32_e32 v9, 0, v4
	v_add_u32_e32 v10, s77, v4
	v_add_u32_e32 v4, s79, v4
	v_mul_u32_u24_e32 v1, 0x640, v1
	v_add_u32_e32 v13, 0, v12
	v_add_u32_e32 v14, s77, v12
	v_add_u32_e32 v12, s79, v12
	v_and_b32_e32 v186, 0xfffffe, v18
	v_and_b32_e32 v188, 0xfffffe, v16
	v_lshlrev_b32_e32 v190, 2, v154
	v_readlane_b32 s0, v246, 35
	v_cmp_gt_i32_e64 s[46:47], s70, v154
	v_lshl_add_u32 v176, v154, 1, 0
	v_ashrrev_i32_e32 v159, 31, v158
	v_ashrrev_i32_e32 v161, 31, v160
	v_ashrrev_i32_e32 v163, 31, v162
	v_lshl_add_u32 v184, v175, 2, s76
	v_cmp_lt_u32_e64 s[52:53], s82, v17
	v_lshl_add_u32 v187, v186, 9, v154
	v_cmp_ne_u32_e64 s[54:55], v18, v186
	v_cmp_lt_u32_e64 s[6:7], s82, v15
	v_lshl_add_u32 v189, v188, 9, v154
	v_cmp_ne_u32_e64 s[4:5], v16, v188
	v_add_u32_e32 v191, s83, v190
	v_add_u32_e32 v193, s86, v190
	v_add_u32_e32 v194, v9, v1
	v_add_u32_e32 v195, v10, v1
	v_add_u32_e32 v196, v4, v1
	v_add_u32_e32 v197, v13, v1
	v_add_u32_e32 v198, v14, v1
	v_add_u32_e32 v199, v12, v1
	v_add_u32_e32 v200, v7, v8
	v_add_u32_e32 v201, v3, v5
	v_add_u32_e32 v202, 0, v2
	v_add_u32_e32 v203, 0, v11
	v_add_u32_e32 v204, v6, v0
	s_mov_b32 s30, s0
	s_mov_b32 s31, s0
	v_readlane_b32 s1, v246, 36
	s_branch .LBB0_817

; DI unsigned xb_add(unsigned* p, unsigned v) { return __hip_atomic_fetch_add(p, v, __ATOMIC_RELAXED, __HIP_MEMORY_SCOPE_AGENT); }
; DI void xcd_barrier(const XcdBarrier& b) {
;     asm volatile("s_waitcnt vmcnt(0)" ::: "memory");
;     __syncthreads();
;     if (threadIdx.x == 0) {
;         unsigned* bar = b.bar;
;         __builtin_amdgcn_s_waitcnt(0);
;         unsigned nloc = b.st[0], nx = b.st[1];
;         if (nloc == 0u) { xcd_barrier_complete(bar, b.x, nloc, nx); b.st[0] = nloc; b.st[1] = nx; }
;         const unsigned old = xb_add(&bar[XB_XSUB(b.x)], 1u);
;         const unsigned gen = old / nloc;
;         if (old + 1u == (gen + 1u) * nloc) {
.LBB0_854:
	s_setprio 0
	s_waitcnt vmcnt(0)
	s_barrier
	s_mov_b64 s[0:1], exec
	v_readlane_b32 s2, v244, 3
	v_readlane_b32 s3, v244, 4
	s_and_b64 s[2:3], s[0:1], s[2:3]
	s_mov_b64 exec, s[2:3]
	s_cbranch_execz .LBB0_813
	v_mov_b32_e32 v0, s96
	s_waitcnt vmcnt(0) expcnt(0) lgkmcnt(0)
	ds_read_b32 v2, v0
	v_mov_b32_e32 v0, s97
	ds_read_b32 v0, v0
	s_waitcnt lgkmcnt(1)
	v_cmp_ne_u32_e32 vcc, 0, v2
	s_cbranch_vccnz .LBB0_870
	s_mov_b32 s10, 1
	s_branch .LBB0_858
